# attention: rescale-test chain shortened (fast path when all lanes are within the threshold, sec 7.12) + one static s_setprio 1 for waves 4-7 (sec 7.4); r1 K-row loads in one round trip
# speedup vs baseline: 1.0080x; 1.0080x over previous
; __device__ __forceinline__ void load_qk16(const Args& a, const bf16_t* __restrict__ src, int hl, int pos, int g, float (&va)[8], float (&vb)[8]) {
;     const u32x4 wa = *(const u32x4*)(src + g * 8), wb = *(const u32x4*)(src + 32 + g * 8);
;     va[0] = bflo(wa.x); va[1] = bfhi(wa.x); va[2] = bflo(wa.y); va[3] = bfhi(wa.y); va[4] = bflo(wa.z); va[5] = bfhi(wa.z); va[6] = bflo(wa.w); va[7] = bfhi(wa.w);
;     vb[0] = bflo(wb.x); vb[1] = bfhi(wb.x); vb[2] = bflo(wb.y); vb[3] = bfhi(wb.y); vb[4] = bflo(wb.z); vb[5] = bfhi(wb.z); vb[6] = bflo(wb.w); vb[7] = bfhi(wb.w);
;     if (hl >= 4) { const f32x2* rp = (const f32x2*)(a.ws + WS_ROPE) + pos * 32 + g * 8;
; #pragma unroll
;         for (int e = 0; e < 8; ++e) { const f32x2 cs = rp[e]; const float x1 = va[e], x2 = vb[e]; va[e] = x1 * cs.x - x2 * cs.y; vb[e] = x1 * cs.y + x2 * cs.x; } }
; }
; __device__ __forceinline__ void r1_item(const Args& a, int L, int item, LAS unsigned char* lds) {
;     ...
;     if (tid < 256) { const int i = (tid >> 2) & 63, g = tid & 3; const int kcol = hl < 4 ? GK + hl * 64 : RK + (hl - 4) * 64;
;         float va[8], vb[8]; load_qk16(a, proj + (R0 + i) * LD + kcol, hl, c * 64 + i, g, va, vb);
.LBB0_174:
	s_andn2_saveexec_b64 s[0:1], s[0:1]
	s_cbranch_execz .LBB0_178
	s_lshl_b32 s24, s14, 6
	s_and_b64 s[8:9], s[8:9], exec
	v_bfe_u32 v2, v34, 2, 6
	s_movk_i32 s8, 0xd00
	s_cselect_b32 s8, s8, 0x1200
	v_or_b32_e32 v0, s10, v2
	v_mov_b64_e32 v[4:5], s[22:23]
	s_add_i32 s24, s8, s24
	s_mul_i32 s10, s11, 0x3200
	v_mad_u64_u32 v[4:5], s[8:9], v0, s79, v[4:5]
	v_lshlrev_b32_e32 v0, 3, v34
	v_add_u32_e32 v5, s10, v5
	s_lshl_b32 s24, s24, 1
	v_and_b32_e32 v29, 24, v0
	v_lshl_add_u64 v[4:5], v[4:5], 0, s[24:25]
	v_lshlrev_b32_e32 v0, 1, v29
	v_lshl_add_u64 v[8:9], v[4:5], 0, v[0:1]
	global_load_dwordx4 v[4:7], v[8:9], off
	global_load_dwordx4 v[14:17], v[8:9], off offset:64
	s_cmp_lt_u32 s14, 4
	s_waitcnt vmcnt(0) lgkmcnt(0)
	v_lshlrev_b32_e32 v10, 16, v7
	v_lshlrev_b32_e32 v26, 16, v4
	v_and_b32_e32 v27, 0xffff0000, v4
	v_lshlrev_b32_e32 v24, 16, v14
	v_and_b32_e32 v25, 0xffff0000, v14
	v_lshlrev_b32_e32 v22, 16, v5
	v_and_b32_e32 v23, 0xffff0000, v5
	v_lshlrev_b32_e32 v20, 16, v15
	v_and_b32_e32 v21, 0xffff0000, v15
	v_lshlrev_b32_e32 v18, 16, v6
	v_and_b32_e32 v19, 0xffff0000, v6
	v_lshlrev_b32_e32 v12, 16, v16
	v_and_b32_e32 v13, 0xffff0000, v16
	v_lshlrev_b32_e32 v16, 16, v17
	v_and_b32_e32 v15, 0xffff0000, v7
	v_and_b32_e32 v14, 0xffff0000, v17
	s_cbranch_scc1 .LBB0_177
	v_or_b32_e32 v0, s5, v2
	v_readlane_b32 s8, v254, 28
	v_lshlrev_b32_e32 v0, 8, v0
	v_readlane_b32 s9, v254, 29
	s_nop 1
	v_lshl_add_u64 v[4:5], s[8:9], 0, v[0:1]
	v_lshlrev_b32_e32 v0, 3, v29
	v_lshl_add_u64 v[8:9], v[4:5], 0, v[0:1]
	global_load_dwordx4 v[4:7], v[8:9], off
	global_load_dwordx4 v[30:33], v[8:9], off offset:16
	global_load_dwordx4 v[36:39], v[8:9], off offset:32
	global_load_dwordx4 v[40:43], v[8:9], off offset:48
	s_waitcnt vmcnt(0) lgkmcnt(0)
	v_mov_b32_e32 v8, v4
	v_mov_b32_e32 v9, v6
	v_mov_b32_e32 v6, v5
	v_mov_b32_e32 v4, v30
	v_mov_b32_e32 v5, v32
	v_mov_b32_e32 v32, v31
	v_mov_b32_e32 v30, v36
	v_mov_b32_e32 v31, v38
	v_mov_b32_e32 v38, v37
	v_mul_f32_e32 v36, v40, v10
	v_mul_f32_e32 v46, v41, v10
	v_pk_mul_f32 v[10:11], v[42:43], v[14:15] op_sel:[0,1] op_sel_hi:[1,0]
	v_pk_mul_f32 v[14:15], v[42:43], v[14:15]
	v_mul_f32_e32 v44, v41, v16
	v_mul_f32_e32 v16, v40, v16
	v_pk_mul_f32 v[40:41], v[6:7], v[24:25]
	v_pk_mul_f32 v[42:43], v[32:33], v[20:21]
	v_pk_mul_f32 v[48:49], v[38:39], v[12:13]
	v_mov_b32_e32 v37, v10
	v_mov_b32_e32 v45, v11
	v_mov_b32_e32 v47, v15
	v_mov_b32_e32 v17, v14
	v_pk_mul_f32 v[24:25], v[8:9], v[24:25]
	v_pk_mul_f32 v[20:21], v[4:5], v[20:21]
	v_pk_mul_f32 v[12:13], v[30:31], v[12:13]
	v_pk_fma_f32 v[8:9], v[8:9], v[26:27], v[40:41] neg_lo:[0,0,1] neg_hi:[0,0,1]
	v_pk_fma_f32 v[4:5], v[4:5], v[22:23], v[42:43] neg_lo:[0,0,1] neg_hi:[0,0,1]
	v_pk_fma_f32 v[30:31], v[30:31], v[18:19], v[48:49] neg_lo:[0,0,1] neg_hi:[0,0,1]
	v_pk_add_f32 v[10:11], v[36:37], v[44:45] neg_lo:[0,1] neg_hi:[0,1]
	v_pk_add_f32 v[16:17], v[46:47], v[16:17]
	v_pk_fma_f32 v[24:25], v[6:7], v[26:27], v[24:25]
	v_pk_fma_f32 v[20:21], v[32:33], v[22:23], v[20:21]
	v_pk_fma_f32 v[12:13], v[38:39], v[18:19], v[12:13]
	v_mov_b32_e32 v14, v17
	v_mov_b32_e32 v26, v8
	v_mov_b32_e32 v27, v9
	v_mov_b32_e32 v22, v4
	v_mov_b32_e32 v23, v5
	v_mov_b32_e32 v18, v30
	v_mov_b32_e32 v19, v31
	v_mov_b32_e32 v15, v11

; #define WAITBAR(N) asm volatile("s_waitcnt vmcnt(" #N ") lgkmcnt(0)\n\ts_barrier" ::: "memory")
; __device__ __forceinline__ void attn_unit(int b, int h, int qb, const bf16_t* __restrict__ proj, const float* __restrict__ btab, float lam, float outscale,
;                                           const float* __restrict__ gain, float* o1scr, bf16_t* merged, LAS char* lds) {
;     ...
;     for (int s = 0; s < 2; ++s) {
;         const int hq = 2 * h + s;
;         const bf16_t* Kh = proj + rowbase * LD + OKK + hq * 64;
;         const bf16_t* Qw = proj + (rowbase + qw + r32) * LD + OQ + hq * 64 + hi * 8;
;         float m_reg = -1e30f, l_reg = 0; f32x16 o[4]; bf16x8 qr[4];
; #pragma unroll
;         for (int d0 = 0; d0 < 4; ++d0) { o[d0] = f32x16{}; qr[d0] = *(const bf16x8*)(Qw + d0 * 16); }
;     ...
;         f32x16 pA0, pA1, pB0, pB1; float mnA, mnB, alA, alB, bo; bf16x8 pa0, pa1, pa2, pa3; constexpr int NT = T / 64;
;         asm volatile("s_waitcnt vmcnt(0) lgkmcnt(0)" ::: "memory"); __syncthreads();
;         DMA_TILE(0, 0); DMA_TILE(1, 1);
;         WAITBAR(3);
.LBB0_187:
	s_or_b32 s24, s6, s48
	s_lshl_b64 s[2:3], s[24:25], 1
	v_lshl_add_u64 v[2:3], v[190:191], 0, s[2:3]
	s_add_u32 s2, s36, s2
	s_addc_u32 s3, s37, s3
	global_load_dwordx4 v[142:145], v[2:3], off
	global_load_dwordx4 v[138:141], v[2:3], off offset:32
	global_load_dwordx4 v[134:137], v[2:3], off offset:64
	global_load_dwordx4 v[130:133], v[2:3], off offset:96
	v_lshl_add_u64 v[184:185], s[2:3], 0, v[186:187]
	s_xor_b64 s[2:3], s[0:1], -1
	s_mov_b64 s[6:7], 0x800
	v_lshl_add_u64 v[184:185], v[184:185], 0, s[6:7]
	v_mov_b64_e32 v[250:251], v[192:193]
	v_mov_b64_e32 v[246:247], v[194:195]
	s_mov_b32 s6, 0xc8000
	s_mov_b32 s7, 0
	v_readfirstlane_b32 s67, v222
	v_add_u32_e32 v239, v226, v227
	v_add_u32_e32 v240, v226, v228
	v_add_u32_e32 v241, v226, v229
	v_add_u32_e32 v242, v226, v230
	s_lshr_b32 s67, s67, 8
	v_add_u32_e32 v239, 0x14000, v239
	v_add_u32_e32 v240, 0x14000, v240
	v_add_u32_e32 v241, 0x14000, v241
	v_add_u32_e32 v242, 0x14000, v242
	v_mov_b32_e32 v243, v215
	v_bfe_u32 v244, v222, 4, 1
	v_bfe_u32 v249, v222, 6, 1
	v_sub_u32_e32 v244, v249, v244
	v_mul_i32_i24_e32 v244, 0xc800, v244
	v_ashrrev_i32_e32 v245, 31, v244
	v_lshl_add_u64 v[250:251], v[250:251], 0, v[244:245]
	v_lshl_add_u64 v[246:247], v[246:247], 0, v[244:245]
	v_mov_b32_e32 v2, 0
	v_mov_b32_e32 v3, 0
	v_mov_b32_e32 v4, 0
	v_mov_b32_e32 v5, 0
	v_mov_b32_e32 v6, 0
	v_mov_b32_e32 v7, 0
	v_mov_b32_e32 v8, 0
	v_mov_b32_e32 v9, 0
	v_mov_b32_e32 v10, 0
	v_mov_b32_e32 v11, 0
	v_mov_b32_e32 v12, 0
	v_mov_b32_e32 v13, 0
	v_mov_b32_e32 v14, 0
	v_mov_b32_e32 v15, 0
	v_mov_b32_e32 v16, 0
	v_mov_b32_e32 v17, 0
	v_mov_b32_e32 v18, 0
	v_mov_b32_e32 v19, 0
	v_mov_b32_e32 v20, 0
	v_mov_b32_e32 v21, 0
	v_mov_b32_e32 v22, 0
	v_mov_b32_e32 v23, 0
	v_mov_b32_e32 v24, 0
	v_mov_b32_e32 v25, 0
	v_mov_b32_e32 v26, 0
	v_mov_b32_e32 v27, 0
	v_mov_b32_e32 v28, 0
	v_mov_b32_e32 v29, 0
	v_mov_b32_e32 v30, 0
	v_mov_b32_e32 v31, 0
	v_mov_b32_e32 v32, 0
	v_mov_b32_e32 v33, 0
	v_mov_b32_e32 v34, 0
	v_mov_b32_e32 v35, 0
	v_mov_b32_e32 v36, 0
	v_mov_b32_e32 v37, 0
	v_mov_b32_e32 v38, 0
	v_mov_b32_e32 v39, 0
	v_mov_b32_e32 v40, 0
	v_mov_b32_e32 v41, 0
	v_mov_b32_e32 v42, 0
	v_mov_b32_e32 v43, 0
	v_mov_b32_e32 v44, 0
	v_mov_b32_e32 v45, 0
	v_mov_b32_e32 v46, 0
	v_mov_b32_e32 v47, 0
	v_mov_b32_e32 v48, 0
	v_mov_b32_e32 v49, 0
	v_mov_b32_e32 v50, 0
	v_mov_b32_e32 v51, 0
	v_mov_b32_e32 v52, 0
	v_mov_b32_e32 v53, 0
	v_mov_b32_e32 v54, 0
	v_mov_b32_e32 v55, 0
	v_mov_b32_e32 v56, 0
	v_mov_b32_e32 v57, 0
	v_mov_b32_e32 v58, 0
	v_mov_b32_e32 v59, 0
	v_mov_b32_e32 v60, 0
	v_mov_b32_e32 v61, 0
	v_mov_b32_e32 v62, 0
	v_mov_b32_e32 v63, 0
	v_mov_b32_e32 v64, 0
	v_mov_b32_e32 v65, 0
	v_mov_b32_e32 v238, 0
	v_add_u32_e32 v245, 0xffffff00, v235
	s_sub_i32 s65, s78, 0x80
	s_mov_b32 s40, 0
	s_waitcnt lgkmcnt(0)
	s_barrier
	s_mov_b32 s24, 0
	s_lshl_b32 s12, s24, 13
	s_add_i32 s12, s12, s66
	s_lshl_b32 s13, s24, 14
	s_add_i32 s13, s13, s74
	s_add_i32 m0, s12, 0x14000
	s_nop 0
	global_load_lds_dwordx4 v[184:185], off
	s_mov_b32 m0, s13
	v_lshl_add_u64 v[184:185], v[184:185], 0, s[6:7]
	global_load_lds_dwordx4 v[250:251], off
	s_add_i32 m0, s13, 0x400
	v_lshl_add_u64 v[250:251], v[250:251], 0, s[6:7]
	global_load_lds_dwordx4 v[246:247], off
	v_lshl_add_u64 v[246:247], v[246:247], 0, s[6:7]
	s_mov_b32 s24, 1
	s_lshl_b32 s12, s24, 13
	s_add_i32 s12, s12, s66
	s_lshl_b32 s13, s24, 14
	s_add_i32 s13, s13, s74
	s_add_i32 m0, s12, 0x14000
	s_nop 0
	global_load_lds_dwordx4 v[184:185], off
	s_mov_b32 m0, s13
	v_lshl_add_u64 v[184:185], v[184:185], 0, s[6:7]
	global_load_lds_dwordx4 v[250:251], off
	s_add_i32 m0, s13, 0x400
	v_lshl_add_u64 v[250:251], v[250:251], 0, s[6:7]
	global_load_lds_dwordx4 v[246:247], off
	v_lshl_add_u64 v[246:247], v[246:247], 0, s[6:7]
	s_waitcnt vmcnt(3)
	s_barrier
	s_cmp_eq_u32 s67, 0
	s_cbranch_scc1 .Lat_enter
	s_barrier
	s_setprio 1

; #define MX3(a, b, c) __builtin_fmaxf(__builtin_fmaxf((a), (b)), (c))
; __device__ __forceinline__ void partialSM(f32x16& p0, f32x16& p1, float& m_reg, float& mn, float& alpha, float boff) {
;     constexpr float C = SCALE * 1.4426950408889634f;
;     float a = MX3(p0[0], p0[1], p1[0]), b = MX3(p0[2], p0[3], p1[1]); a = MX3(a, p1[2], p1[3]);
; #pragma unroll
;     for (int r = 4; r < 16; r += 4) { a = MX3(a, p0[r], p0[r + 1]); b = MX3(b, p0[r + 2], p0[r + 3]); a = MX3(a, p1[r], p1[r + 1]); b = MX3(b, p1[r + 2], p1[r + 3]); }
;     float pmax = __builtin_fmaxf(a, b);
;     { auto rr = __builtin_amdgcn_permlane32_swap(__float_as_uint(pmax), __float_as_uint(pmax), false, false);
;       pmax = fmaxf(__uint_as_float(rr[0]), __uint_as_float(rr[1])) + boff; }
;     if (__builtin_expect(__all(pmax - m_reg <= THR / SCALE), 1)) { mn = m_reg; alpha = 1.f; }
;     else { mn = fmaxf(m_reg, pmax); alpha = __builtin_amdgcn_exp2f((m_reg - mn) * C); m_reg = mn; }
;     const float mnC = (boff - mn) * C;
; #pragma unroll
;     for (int r = 0; r < 16; ++r) p0[r] = fmaf(p0[r], C, mnC);
; #pragma unroll
;     for (int r = 0; r < 16; ++r) p1[r] = fmaf(p1[r], C, mnC);
; #pragma unroll
;     for (int r = 0; r < 16; ++r) p0[r] = __builtin_amdgcn_exp2f(p0[r]);
; }
; __device__ __forceinline__ void finishSM(f32x16& p0, f32x16& p1, float alpha, float& l_reg, bf16x8& pa0, bf16x8& pa1, bf16x8& pa2, bf16x8& pa3) {
; #pragma unroll
;     for (int r = 0; r < 16; ++r) p1[r] = __builtin_amdgcn_exp2f(p1[r]);
;     float ps = 0;
; #pragma unroll
;     for (int r = 0; r < 16; ++r) ps += p0[r];
; #pragma unroll
;     for (int r = 0; r < 16; ++r) ps += p1[r];
;     { auto rr = __builtin_amdgcn_permlane32_swap(__float_as_uint(ps), __float_as_uint(ps), false, false);
;       ps = __uint_as_float(rr[0]) + __uint_as_float(rr[1]); }
;     l_reg = l_reg * alpha + ps;
;     ...
;     PK4(p0, 0, pa0); PK4(p0, 8, pa1); PK4(p1, 0, pa2); PK4(p1, 8, pa3);
;     ...
; }
.Lat_qkd_p:
	s_nop 15
	s_waitcnt vmcnt(3)
	s_barrier
	v_max_f32_e32 v244, v82, v83
	v_max3_f32 v249, v84, v85, v67
	v_max3_f32 v244, v244, v66, v68
	v_max3_f32 v244, v244, v69, v86
	v_max3_f32 v249, v249, v88, v89
	v_max3_f32 v244, v244, v87, v70
	v_max3_f32 v249, v249, v72, v73
	v_max3_f32 v244, v244, v71, v90
	v_max3_f32 v249, v249, v92, v93
	v_max3_f32 v244, v244, v91, v74
	v_max3_f32 v249, v249, v76, v77
	v_max3_f32 v244, v244, v75, v94
	v_max3_f32 v249, v249, v96, v97
	v_max3_f32 v244, v244, v95, v78
	v_max3_f32 v249, v249, v80, v81
	v_max3_f32 v244, v244, v79, v249
	v_mov_b32_e32 v249, v244
	s_nop 1
	v_permlane32_swap_b32_e32 v244, v249
	v_max_f32_e32 v244, v244, v249
	v_add_f32_e32 v244, v0, v244
	v_sub_f32_e32 v249, v244, v243
	v_cmp_ge_f32_e32 vcc, s72, v249
	v_max_f32_e32 v249, v243, v244
	s_cmp_eq_u64 vcc, exec
	s_cbranch_scc1 .Lat_noresc_p
	v_sub_f32_e32 v220, v243, v249
	v_mul_f32_e32 v220, 0x3e38aa3b, v220
	v_exp_f32_e32 v248, v220
	v_mov_b32_e32 v243, v249
	s_nop 0
	v_mul_f32_e32 v238, v238, v248
	s_and_saveexec_b64 s[12:13], s[38:39]
	ds_write_b32 v232, v248 offset:128
	s_or_b64 exec, exec, s[12:13]
	s_waitcnt lgkmcnt(0)
	v_add_u32_e32 v110, s31, v188
	ds_read_b128 v[98:101], v110 offset:224
	ds_read_b128 v[102:105], v110 offset:192
	ds_read_b128 v[106:109], v110 offset:160
	ds_read_b128 v[110:113], v110 offset:128
	s_waitcnt lgkmcnt(0)
	v_pk_mul_f32 v[62:63], v[62:63], v[98:99]
	v_pk_mul_f32 v[58:59], v[58:59], v[102:103]
	v_pk_mul_f32 v[54:55], v[54:55], v[106:107]
	v_pk_mul_f32 v[64:65], v[64:65], v[100:101]
	v_pk_mul_f32 v[60:61], v[60:61], v[104:105]
	v_pk_mul_f32 v[56:57], v[56:57], v[108:109]
	v_pk_mul_f32 v[52:53], v[52:53], v[112:113]
	v_pk_mul_f32 v[50:51], v[50:51], v[110:111]
	v_pk_mul_f32 v[46:47], v[46:47], v[98:99]
	v_pk_mul_f32 v[42:43], v[42:43], v[102:103]
	v_pk_mul_f32 v[38:39], v[38:39], v[106:107]
	v_pk_mul_f32 v[48:49], v[48:49], v[100:101]
	v_pk_mul_f32 v[44:45], v[44:45], v[104:105]
	v_pk_mul_f32 v[40:41], v[40:41], v[108:109]
	v_pk_mul_f32 v[36:37], v[36:37], v[112:113]
	v_pk_mul_f32 v[34:35], v[34:35], v[110:111]
	v_pk_mul_f32 v[30:31], v[30:31], v[98:99]
	v_pk_mul_f32 v[26:27], v[26:27], v[102:103]
	v_pk_mul_f32 v[22:23], v[22:23], v[106:107]
	v_pk_mul_f32 v[32:33], v[32:33], v[100:101]
	v_pk_mul_f32 v[28:29], v[28:29], v[104:105]
	v_pk_mul_f32 v[24:25], v[24:25], v[108:109]
	v_pk_mul_f32 v[20:21], v[20:21], v[112:113]
	v_pk_mul_f32 v[18:19], v[18:19], v[110:111]
	v_pk_mul_f32 v[14:15], v[14:15], v[98:99]
	v_pk_mul_f32 v[10:11], v[10:11], v[102:103]
	v_pk_mul_f32 v[6:7], v[6:7], v[106:107]
	v_pk_mul_f32 v[16:17], v[16:17], v[100:101]
	v_pk_mul_f32 v[12:13], v[12:13], v[104:105]
	v_pk_mul_f32 v[8:9], v[8:9], v[108:109]
	v_pk_mul_f32 v[4:5], v[4:5], v[112:113]
	v_pk_mul_f32 v[2:3], v[2:3], v[110:111]
.Lat_noresc_p:
	v_sub_f32_e32 v0, v0, v243
	v_mul_f32_e32 v0, 0x3e38aa3b, v0
	v_fmamk_f32 v82, v82, 0x3e38aa3b, v0
	v_fmamk_f32 v83, v83, 0x3e38aa3b, v0
	v_fmamk_f32 v84, v84, 0x3e38aa3b, v0
	v_fmamk_f32 v85, v85, 0x3e38aa3b, v0
	v_fmamk_f32 v86, v86, 0x3e38aa3b, v0
	v_fmamk_f32 v87, v87, 0x3e38aa3b, v0
	v_fmamk_f32 v88, v88, 0x3e38aa3b, v0
	v_fmamk_f32 v89, v89, 0x3e38aa3b, v0
	v_fmamk_f32 v90, v90, 0x3e38aa3b, v0
	v_fmamk_f32 v91, v91, 0x3e38aa3b, v0
	v_fmamk_f32 v92, v92, 0x3e38aa3b, v0
	v_fmamk_f32 v93, v93, 0x3e38aa3b, v0
	v_fmamk_f32 v94, v94, 0x3e38aa3b, v0
	v_fmamk_f32 v95, v95, 0x3e38aa3b, v0
	v_fmamk_f32 v96, v96, 0x3e38aa3b, v0
	v_fmamk_f32 v97, v97, 0x3e38aa3b, v0
	v_fmamk_f32 v66, v66, 0x3e38aa3b, v0
	v_fmamk_f32 v67, v67, 0x3e38aa3b, v0
	v_fmamk_f32 v68, v68, 0x3e38aa3b, v0
	v_fmamk_f32 v69, v69, 0x3e38aa3b, v0
	v_fmamk_f32 v70, v70, 0x3e38aa3b, v0
	v_fmamk_f32 v71, v71, 0x3e38aa3b, v0
	v_fmamk_f32 v72, v72, 0x3e38aa3b, v0
	v_fmamk_f32 v73, v73, 0x3e38aa3b, v0
	v_fmamk_f32 v74, v74, 0x3e38aa3b, v0
	v_fmamk_f32 v75, v75, 0x3e38aa3b, v0
	v_fmamk_f32 v76, v76, 0x3e38aa3b, v0
	v_fmamk_f32 v77, v77, 0x3e38aa3b, v0
	v_fmamk_f32 v78, v78, 0x3e38aa3b, v0
	v_fmamk_f32 v79, v79, 0x3e38aa3b, v0
	v_fmamk_f32 v80, v80, 0x3e38aa3b, v0
	v_fmamk_f32 v81, v81, 0x3e38aa3b, v0
	v_exp_f32_e32 v82, v82
	v_exp_f32_e32 v83, v83
	v_exp_f32_e32 v84, v84
	v_exp_f32_e32 v85, v85
	v_exp_f32_e32 v86, v86
	v_exp_f32_e32 v87, v87
	v_exp_f32_e32 v88, v88
	v_exp_f32_e32 v89, v89
	v_exp_f32_e32 v90, v90
	v_exp_f32_e32 v91, v91
	v_exp_f32_e32 v92, v92
	v_exp_f32_e32 v93, v93
	v_exp_f32_e32 v94, v94
	v_exp_f32_e32 v95, v95
	v_exp_f32_e32 v96, v96
	v_exp_f32_e32 v97, v97
	v_exp_f32_e32 v66, v66
	v_add_f32_e32 v244, v82, v83
	v_exp_f32_e32 v67, v67
	v_add_f32_e32 v244, v84, v244
	v_exp_f32_e32 v68, v68
	v_add_f32_e32 v244, v85, v244
	v_exp_f32_e32 v69, v69
	v_add_f32_e32 v244, v86, v244
	v_exp_f32_e32 v70, v70
	v_add_f32_e32 v244, v87, v244
	v_exp_f32_e32 v71, v71
	v_add_f32_e32 v244, v88, v244
	v_exp_f32_e32 v72, v72
	v_add_f32_e32 v244, v89, v244
	v_exp_f32_e32 v73, v73
	v_add_f32_e32 v244, v90, v244
	v_exp_f32_e32 v74, v74
	v_add_f32_e32 v244, v91, v244
	v_exp_f32_e32 v75, v75
	v_add_f32_e32 v244, v92, v244
	v_exp_f32_e32 v76, v76
	v_add_f32_e32 v244, v93, v244
	v_exp_f32_e32 v77, v77
	v_add_f32_e32 v244, v94, v244
	v_exp_f32_e32 v78, v78
	v_add_f32_e32 v244, v95, v244
	v_exp_f32_e32 v79, v79
	v_add_f32_e32 v244, v96, v244
	v_exp_f32_e32 v80, v80
	v_add_f32_e32 v244, v97, v244
	v_exp_f32_e32 v81, v81
	v_add_f32_e32 v249, v66, v67
	v_add_f32_e32 v249, v68, v249
	v_add_f32_e32 v249, v69, v249
	v_add_f32_e32 v249, v70, v249
	v_add_f32_e32 v249, v71, v249
	v_add_f32_e32 v249, v72, v249
	v_add_f32_e32 v249, v73, v249
	v_add_f32_e32 v249, v74, v249
	v_add_f32_e32 v249, v75, v249
	v_add_f32_e32 v249, v76, v249
	v_add_f32_e32 v249, v77, v249
	v_add_f32_e32 v249, v78, v249
	v_add_f32_e32 v249, v79, v249
	v_add_f32_e32 v249, v80, v249
	v_add_f32_e32 v249, v81, v249
	v_add_f32_e32 v244, v244, v249
	v_add_f32_e32 v238, v238, v244
	v_cvt_pk_bf16_f32 v146, v82, v83
	v_cvt_pk_bf16_f32 v147, v84, v85
	v_cvt_pk_bf16_f32 v148, v86, v87
	v_cvt_pk_bf16_f32 v149, v88, v89
	v_cvt_pk_bf16_f32 v150, v90, v91
	v_cvt_pk_bf16_f32 v151, v92, v93
	v_cvt_pk_bf16_f32 v152, v94, v95
	v_cvt_pk_bf16_f32 v153, v96, v97
	v_cvt_pk_bf16_f32 v154, v66, v67
	v_cvt_pk_bf16_f32 v155, v68, v69
	v_cvt_pk_bf16_f32 v156, v70, v71
	v_cvt_pk_bf16_f32 v157, v72, v73
	v_cvt_pk_bf16_f32 v158, v74, v75
	v_cvt_pk_bf16_f32 v159, v76, v77
	v_cvt_pk_bf16_f32 v160, v78, v79
	v_cvt_pk_bf16_f32 v161, v80, v81
	s_add_i32 s40, s40, 1
	s_addk_i32 s65, 0x40
	v_add_u32_e32 v245, 0x100, v245
	s_barrier

; #define MX3(a, b, c) __builtin_fmaxf(__builtin_fmaxf((a), (b)), (c))
; __device__ __forceinline__ void partialSM(f32x16& p0, f32x16& p1, float& m_reg, float& mn, float& alpha, float boff) {
;     constexpr float C = SCALE * 1.4426950408889634f;
;     float a = MX3(p0[0], p0[1], p1[0]), b = MX3(p0[2], p0[3], p1[1]); a = MX3(a, p1[2], p1[3]);
; #pragma unroll
;     for (int r = 4; r < 16; r += 4) { a = MX3(a, p0[r], p0[r + 1]); b = MX3(b, p0[r + 2], p0[r + 3]); a = MX3(a, p1[r], p1[r + 1]); b = MX3(b, p1[r + 2], p1[r + 3]); }
;     float pmax = __builtin_fmaxf(a, b);
;     { auto rr = __builtin_amdgcn_permlane32_swap(__float_as_uint(pmax), __float_as_uint(pmax), false, false);
;       pmax = fmaxf(__uint_as_float(rr[0]), __uint_as_float(rr[1])) + boff; }
;     if (__builtin_expect(__all(pmax - m_reg <= THR / SCALE), 1)) { mn = m_reg; alpha = 1.f; }
;     else { mn = fmaxf(m_reg, pmax); alpha = __builtin_amdgcn_exp2f((m_reg - mn) * C); m_reg = mn; }
;     const float mnC = (boff - mn) * C;
; #pragma unroll
;     for (int r = 0; r < 16; ++r) p0[r] = fmaf(p0[r], C, mnC);
; #pragma unroll
;     for (int r = 0; r < 16; ++r) p1[r] = fmaf(p1[r], C, mnC);
; #pragma unroll
;     for (int r = 0; r < 16; ++r) p0[r] = __builtin_amdgcn_exp2f(p0[r]);
; }
; __device__ __forceinline__ void finishSM(f32x16& p0, f32x16& p1, float alpha, float& l_reg, bf16x8& pa0, bf16x8& pa1, bf16x8& pa2, bf16x8& pa3) {
; #pragma unroll
;     for (int r = 0; r < 16; ++r) p1[r] = __builtin_amdgcn_exp2f(p1[r]);
;     float ps = 0;
; #pragma unroll
;     for (int r = 0; r < 16; ++r) ps += p0[r];
; #pragma unroll
;     for (int r = 0; r < 16; ++r) ps += p1[r];
;     { auto rr = __builtin_amdgcn_permlane32_swap(__float_as_uint(ps), __float_as_uint(ps), false, false);
;       ps = __uint_as_float(rr[0]) + __uint_as_float(rr[1]); }
;     l_reg = l_reg * alpha + ps;
;     ...
;     PK4(p0, 0, pa0); PK4(p0, 8, pa1); PK4(p1, 0, pa2); PK4(p1, 8, pa3);
;     ...
; }
.Lat_wd_l:
	s_barrier
	v_max_f32_e32 v244, v82, v83
	v_max3_f32 v249, v84, v85, v67
	v_max3_f32 v244, v244, v66, v68
	v_max3_f32 v244, v244, v69, v86
	v_max3_f32 v249, v249, v88, v89
	v_max3_f32 v244, v244, v87, v70
	v_max3_f32 v249, v249, v72, v73
	v_max3_f32 v244, v244, v71, v90
	v_max3_f32 v249, v249, v92, v93
	v_max3_f32 v244, v244, v91, v74
	v_max3_f32 v249, v249, v76, v77
	v_max3_f32 v244, v244, v75, v94
	v_max3_f32 v249, v249, v96, v97
	v_max3_f32 v244, v244, v95, v78
	v_max3_f32 v249, v249, v80, v81
	v_max3_f32 v244, v244, v79, v249
	v_mov_b32_e32 v249, v244
	s_nop 1
	v_permlane32_swap_b32_e32 v244, v249
	v_max_f32_e32 v244, v244, v249
	v_add_f32_e32 v244, v0, v244
	v_sub_f32_e32 v249, v244, v243
	v_cmp_ge_f32_e32 vcc, s72, v249
	v_max_f32_e32 v249, v243, v244
	s_cmp_eq_u64 vcc, exec
	s_cbranch_scc1 .Lat_noresc_l
	v_sub_f32_e32 v220, v243, v249
	v_mul_f32_e32 v220, 0x3e38aa3b, v220
	v_exp_f32_e32 v248, v220
	v_mov_b32_e32 v243, v249
	s_nop 0
	v_mul_f32_e32 v238, v238, v248
	s_and_saveexec_b64 s[12:13], s[38:39]
	ds_write_b32 v232, v248 offset:128
	s_or_b64 exec, exec, s[12:13]
	s_waitcnt lgkmcnt(0)
	v_add_u32_e32 v110, s31, v188
	ds_read_b128 v[98:101], v110 offset:224
	ds_read_b128 v[102:105], v110 offset:192
	ds_read_b128 v[106:109], v110 offset:160
	ds_read_b128 v[110:113], v110 offset:128
	s_waitcnt lgkmcnt(0)
	v_pk_mul_f32 v[62:63], v[62:63], v[98:99]
	v_pk_mul_f32 v[58:59], v[58:59], v[102:103]
	v_pk_mul_f32 v[54:55], v[54:55], v[106:107]
	v_pk_mul_f32 v[64:65], v[64:65], v[100:101]
	v_pk_mul_f32 v[60:61], v[60:61], v[104:105]
	v_pk_mul_f32 v[56:57], v[56:57], v[108:109]
	v_pk_mul_f32 v[52:53], v[52:53], v[112:113]
	v_pk_mul_f32 v[50:51], v[50:51], v[110:111]
	v_pk_mul_f32 v[46:47], v[46:47], v[98:99]
	v_pk_mul_f32 v[42:43], v[42:43], v[102:103]
	v_pk_mul_f32 v[38:39], v[38:39], v[106:107]
	v_pk_mul_f32 v[48:49], v[48:49], v[100:101]
	v_pk_mul_f32 v[44:45], v[44:45], v[104:105]
	v_pk_mul_f32 v[40:41], v[40:41], v[108:109]
	v_pk_mul_f32 v[36:37], v[36:37], v[112:113]
	v_pk_mul_f32 v[34:35], v[34:35], v[110:111]
	v_pk_mul_f32 v[30:31], v[30:31], v[98:99]
	v_pk_mul_f32 v[26:27], v[26:27], v[102:103]
	v_pk_mul_f32 v[22:23], v[22:23], v[106:107]
	v_pk_mul_f32 v[32:33], v[32:33], v[100:101]
	v_pk_mul_f32 v[28:29], v[28:29], v[104:105]
	v_pk_mul_f32 v[24:25], v[24:25], v[108:109]
	v_pk_mul_f32 v[20:21], v[20:21], v[112:113]
	v_pk_mul_f32 v[18:19], v[18:19], v[110:111]
	v_pk_mul_f32 v[14:15], v[14:15], v[98:99]
	v_pk_mul_f32 v[10:11], v[10:11], v[102:103]
	v_pk_mul_f32 v[6:7], v[6:7], v[106:107]
	v_pk_mul_f32 v[16:17], v[16:17], v[100:101]
	v_pk_mul_f32 v[12:13], v[12:13], v[104:105]
	v_pk_mul_f32 v[8:9], v[8:9], v[108:109]
	v_pk_mul_f32 v[4:5], v[4:5], v[112:113]
	v_pk_mul_f32 v[2:3], v[2:3], v[110:111]
.Lat_noresc_l:
	v_sub_f32_e32 v0, v0, v243
	v_mul_f32_e32 v0, 0x3e38aa3b, v0
	v_fmamk_f32 v82, v82, 0x3e38aa3b, v0
	v_fmamk_f32 v83, v83, 0x3e38aa3b, v0
	v_fmamk_f32 v84, v84, 0x3e38aa3b, v0
	v_fmamk_f32 v85, v85, 0x3e38aa3b, v0
	v_fmamk_f32 v86, v86, 0x3e38aa3b, v0
	v_fmamk_f32 v87, v87, 0x3e38aa3b, v0
	v_fmamk_f32 v88, v88, 0x3e38aa3b, v0
	v_fmamk_f32 v89, v89, 0x3e38aa3b, v0
	v_fmamk_f32 v90, v90, 0x3e38aa3b, v0
	v_fmamk_f32 v91, v91, 0x3e38aa3b, v0
	v_fmamk_f32 v92, v92, 0x3e38aa3b, v0
	v_fmamk_f32 v93, v93, 0x3e38aa3b, v0
	v_fmamk_f32 v94, v94, 0x3e38aa3b, v0
	v_fmamk_f32 v95, v95, 0x3e38aa3b, v0
	v_fmamk_f32 v96, v96, 0x3e38aa3b, v0
	v_fmamk_f32 v97, v97, 0x3e38aa3b, v0
	v_fmamk_f32 v66, v66, 0x3e38aa3b, v0
	v_fmamk_f32 v67, v67, 0x3e38aa3b, v0
	v_fmamk_f32 v68, v68, 0x3e38aa3b, v0
	v_fmamk_f32 v69, v69, 0x3e38aa3b, v0
	v_fmamk_f32 v70, v70, 0x3e38aa3b, v0
	v_fmamk_f32 v71, v71, 0x3e38aa3b, v0
	v_fmamk_f32 v72, v72, 0x3e38aa3b, v0
	v_fmamk_f32 v73, v73, 0x3e38aa3b, v0
	v_fmamk_f32 v74, v74, 0x3e38aa3b, v0
	v_fmamk_f32 v75, v75, 0x3e38aa3b, v0
	v_fmamk_f32 v76, v76, 0x3e38aa3b, v0
	v_fmamk_f32 v77, v77, 0x3e38aa3b, v0
	v_fmamk_f32 v78, v78, 0x3e38aa3b, v0
	v_fmamk_f32 v79, v79, 0x3e38aa3b, v0
	v_fmamk_f32 v80, v80, 0x3e38aa3b, v0
	v_fmamk_f32 v81, v81, 0x3e38aa3b, v0
	v_exp_f32_e32 v82, v82
	v_exp_f32_e32 v83, v83
	v_exp_f32_e32 v84, v84
	v_exp_f32_e32 v85, v85
	v_exp_f32_e32 v86, v86
	v_exp_f32_e32 v87, v87
	v_exp_f32_e32 v88, v88
	v_exp_f32_e32 v89, v89
	v_exp_f32_e32 v90, v90
	v_exp_f32_e32 v91, v91
	v_exp_f32_e32 v92, v92
	v_exp_f32_e32 v93, v93
	v_exp_f32_e32 v94, v94
	v_exp_f32_e32 v95, v95
	v_exp_f32_e32 v96, v96
	v_exp_f32_e32 v97, v97
	v_exp_f32_e32 v66, v66
	v_add_f32_e32 v244, v82, v83
	v_exp_f32_e32 v67, v67
	v_add_f32_e32 v244, v84, v244
	v_exp_f32_e32 v68, v68
	v_add_f32_e32 v244, v85, v244
	v_exp_f32_e32 v69, v69
	v_add_f32_e32 v244, v86, v244
	v_exp_f32_e32 v70, v70
	v_add_f32_e32 v244, v87, v244
	v_exp_f32_e32 v71, v71
	v_add_f32_e32 v244, v88, v244
	v_exp_f32_e32 v72, v72
	v_add_f32_e32 v244, v89, v244
	v_exp_f32_e32 v73, v73
	v_add_f32_e32 v244, v90, v244
	v_exp_f32_e32 v74, v74
	v_add_f32_e32 v244, v91, v244
	v_exp_f32_e32 v75, v75
	v_add_f32_e32 v244, v92, v244
	v_exp_f32_e32 v76, v76
	v_add_f32_e32 v244, v93, v244
	v_exp_f32_e32 v77, v77
	v_add_f32_e32 v244, v94, v244
	v_exp_f32_e32 v78, v78
	v_add_f32_e32 v244, v95, v244
	v_exp_f32_e32 v79, v79
	v_add_f32_e32 v244, v96, v244
	v_exp_f32_e32 v80, v80
	v_add_f32_e32 v244, v97, v244
	v_exp_f32_e32 v81, v81
	v_add_f32_e32 v249, v66, v67
	v_add_f32_e32 v249, v68, v249
	v_add_f32_e32 v249, v69, v249
	v_add_f32_e32 v249, v70, v249
	v_add_f32_e32 v249, v71, v249
	v_add_f32_e32 v249, v72, v249
	v_add_f32_e32 v249, v73, v249
	v_add_f32_e32 v249, v74, v249
	v_add_f32_e32 v249, v75, v249
	v_add_f32_e32 v249, v76, v249
	v_add_f32_e32 v249, v77, v249
	v_add_f32_e32 v249, v78, v249
	v_add_f32_e32 v249, v79, v249
	v_add_f32_e32 v249, v80, v249
	v_add_f32_e32 v249, v81, v249
	v_add_f32_e32 v244, v244, v249
	v_add_f32_e32 v238, v238, v244
	v_cvt_pk_bf16_f32 v146, v82, v83
	v_cvt_pk_bf16_f32 v147, v84, v85
	v_cvt_pk_bf16_f32 v148, v86, v87
	v_cvt_pk_bf16_f32 v149, v88, v89
	v_cvt_pk_bf16_f32 v150, v90, v91
	v_cvt_pk_bf16_f32 v151, v92, v93
	v_cvt_pk_bf16_f32 v152, v94, v95
	v_cvt_pk_bf16_f32 v153, v96, v97
	v_cvt_pk_bf16_f32 v154, v66, v67
	v_cvt_pk_bf16_f32 v155, v68, v69
	v_cvt_pk_bf16_f32 v156, v70, v71
	v_cvt_pk_bf16_f32 v157, v72, v73
	v_cvt_pk_bf16_f32 v158, v74, v75
	v_cvt_pk_bf16_f32 v159, v76, v77
	v_cvt_pk_bf16_f32 v160, v78, v79
	v_cvt_pk_bf16_f32 v161, v80, v81
	s_add_i32 s40, s40, 1
	s_addk_i32 s65, 0x40
	v_add_u32_e32 v245, 0x100, v245
	s_barrier
; #define SBAR() __builtin_amdgcn_sched_barrier(0)
; __device__ __forceinline__ int crow(int r, int hi) { return (r & 3) + 8 * (r >> 2) + 4 * hi; }
; __device__ __forceinline__ int crow(int r, int hi) { return (r & 3) + 8 * (r >> 2) + 4 * hi; }
; template <int D0> __device__ __forceinline__ void pv_one(f32x16& od, int vb, bf16x8 pa0, bf16x8 pa1, bf16x8 pa2, bf16x8 pa3) {
;     const s16x4 l0 = tr_read<v_rd_off(D0, 0, 0)>(vb), h0 = tr_read<v_rd_off(D0, 0, 1)>(vb), l1 = tr_read<v_rd_off(D0, 1, 0)>(vb), h1 = tr_read<v_rd_off(D0, 1, 1)>(vb);
;     const s16x4 l2 = tr_read<v_rd_off(D0, 2, 0)>(vb), h2 = tr_read<v_rd_off(D0, 2, 1)>(vb), l3 = tr_read<v_rd_off(D0, 3, 0)>(vb), h3 = tr_read<v_rd_off(D0, 3, 1)>(vb);
;     asm volatile("s_waitcnt lgkmcnt(0)" ::: "memory"); SBAR();
;     ...
;     od = __builtin_amdgcn_mfma_f32_32x32x16_bf16(pa0, PK(l0, h0), od, 0, 0, 0);
;     od = __builtin_amdgcn_mfma_f32_32x32x16_bf16(pa1, PK(l1, h1), od, 0, 0, 0);
;     od = __builtin_amdgcn_mfma_f32_32x32x16_bf16(pa2, PK(l2, h2), od, 0, 0, 0);
;     od = __builtin_amdgcn_mfma_f32_32x32x16_bf16(pa3, PK(l3, h3), od, 0, 0, 0);
;     ...
; }
; __device__ __forceinline__ void pv_d0(f32x16* o, int vb, bf16x8 pa0, bf16x8 pa1, bf16x8 pa2, bf16x8 pa3) {
;     pv_one<0>(o[0], vb, pa0, pa1, pa2, pa3); pv_one<1>(o[1], vb, pa0, pa1, pa2, pa3); pv_one<2>(o[2], vb, pa0, pa1, pa2, pa3); pv_one<3>(o[3], vb, pa0, pa1, pa2, pa3);
; __device__ __forceinline__ void attn_unit(int b, int h, int qb, const bf16_t* __restrict__ proj, const float* __restrict__ btab, float lam, float outscale,
;                                           const float* __restrict__ gain, float* o1scr, bf16_t* merged, LAS char* lds) {
;     ...
;         if (hi == 0) li_l[r32] = l_reg; asm volatile("s_waitcnt lgkmcnt(0)" ::: "memory");
;         float rli[16];
; #pragma unroll
;         for (int r = 0; r < 16; ++r) rli[r] = __builtin_amdgcn_rcpf(li_l[crow(r, hi)]);
	s_cmp_lt_u32 s40, 64
	s_cbranch_scc1 .Lat_loop
	s_add_i32 s54, s40, 3
	s_and_b32 s54, s54, 3
	s_lshl_b32 s54, s54, 14
	v_add_u32_e32 v244, s54, v225
	ds_read_b64_tr_b16 v[162:163], v244 offset:0x0
	ds_read_b64_tr_b16 v[164:165], v244 offset:0x800
	ds_read_b64_tr_b16 v[166:167], v244 offset:0x1000
	ds_read_b64_tr_b16 v[168:169], v244 offset:0x1800
	ds_read_b64_tr_b16 v[170:171], v244 offset:0x2000
	ds_read_b64_tr_b16 v[172:173], v244 offset:0x2800
	ds_read_b64_tr_b16 v[174:175], v244 offset:0x3000
	ds_read_b64_tr_b16 v[176:177], v244 offset:0x3800
	s_waitcnt lgkmcnt(0)
	v_mfma_f32_32x32x16_bf16 v[50:65], v[146:149], v[162:165], v[50:65]
	ds_read_b64_tr_b16 v[162:163], v244 offset:0x200
	ds_read_b64_tr_b16 v[164:165], v244 offset:0xa00
	v_mfma_f32_32x32x16_bf16 v[50:65], v[150:153], v[166:169], v[50:65]
	ds_read_b64_tr_b16 v[166:167], v244 offset:0x1200
	ds_read_b64_tr_b16 v[168:169], v244 offset:0x1a00
	v_mfma_f32_32x32x16_bf16 v[50:65], v[154:157], v[170:173], v[50:65]
	ds_read_b64_tr_b16 v[170:171], v244 offset:0x2200
	ds_read_b64_tr_b16 v[172:173], v244 offset:0x2a00
	v_mfma_f32_32x32x16_bf16 v[50:65], v[158:161], v[174:177], v[50:65]
	ds_read_b64_tr_b16 v[174:175], v244 offset:0x3200
	ds_read_b64_tr_b16 v[176:177], v244 offset:0x3a00
	s_waitcnt lgkmcnt(0)
	v_mfma_f32_32x32x16_bf16 v[34:49], v[146:149], v[162:165], v[34:49]
	ds_read_b64_tr_b16 v[162:163], v244 offset:0x400
	ds_read_b64_tr_b16 v[164:165], v244 offset:0xc00
	v_mfma_f32_32x32x16_bf16 v[34:49], v[150:153], v[166:169], v[34:49]
	ds_read_b64_tr_b16 v[166:167], v244 offset:0x1400
	ds_read_b64_tr_b16 v[168:169], v244 offset:0x1c00
	v_mfma_f32_32x32x16_bf16 v[34:49], v[154:157], v[170:173], v[34:49]
	ds_read_b64_tr_b16 v[170:171], v244 offset:0x2400
	ds_read_b64_tr_b16 v[172:173], v244 offset:0x2c00
	v_mfma_f32_32x32x16_bf16 v[34:49], v[158:161], v[174:177], v[34:49]
	ds_read_b64_tr_b16 v[174:175], v244 offset:0x3400
	ds_read_b64_tr_b16 v[176:177], v244 offset:0x3c00
	s_waitcnt lgkmcnt(0)
	v_mfma_f32_32x32x16_bf16 v[18:33], v[146:149], v[162:165], v[18:33]
	ds_read_b64_tr_b16 v[162:163], v244 offset:0x600
	ds_read_b64_tr_b16 v[164:165], v244 offset:0xe00
	v_mfma_f32_32x32x16_bf16 v[18:33], v[150:153], v[166:169], v[18:33]
	ds_read_b64_tr_b16 v[166:167], v244 offset:0x1600
	ds_read_b64_tr_b16 v[168:169], v244 offset:0x1e00
	v_mfma_f32_32x32x16_bf16 v[18:33], v[154:157], v[170:173], v[18:33]
	ds_read_b64_tr_b16 v[170:171], v244 offset:0x2600
	ds_read_b64_tr_b16 v[172:173], v244 offset:0x2e00
	v_mfma_f32_32x32x16_bf16 v[18:33], v[158:161], v[174:177], v[18:33]
	ds_read_b64_tr_b16 v[174:175], v244 offset:0x3600
	ds_read_b64_tr_b16 v[176:177], v244 offset:0x3e00
	s_waitcnt lgkmcnt(0)
	v_mfma_f32_32x32x16_bf16 v[2:17], v[146:149], v[162:165], v[2:17]
	v_mfma_f32_32x32x16_bf16 v[2:17], v[150:153], v[166:169], v[2:17]
	v_mfma_f32_32x32x16_bf16 v[2:17], v[154:157], v[170:173], v[2:17]
	v_mfma_f32_32x32x16_bf16 v[2:17], v[158:161], v[174:177], v[2:17]
	s_cmp_lg_u32 s67, 0
	s_cbranch_scc1 .Lat_fin
	s_barrier
.Lat_fin:
	s_setprio 0
	v_mov_b32_e32 v244, v238
	s_nop 1
	v_permlane32_swap_b32_e32 v238, v244
	v_add_f32_e32 v66, v238, v244
	s_and_saveexec_b64 s[0:1], s[38:39]
	ds_write_b32 v232, v66
	s_or_b64 exec, exec, s[0:1]
	s_waitcnt lgkmcnt(0)
	v_add_u32_e32 v0, s31, v188
	ds_read_b128 v[66:69], v0
	ds_read_b128 v[70:73], v0 offset:32
	v_mov_b32_e32 v88, v222
	s_andn2_b64 vcc, exec, s[2:3]
	s_mov_b64 s[0:1], -1
	s_waitcnt lgkmcnt(0)
	v_rcp_f32_e32 v86, v66
	v_rcp_f32_e32 v87, v67
	v_rcp_f32_e32 v84, v68
	v_rcp_f32_e32 v85, v69
	ds_read_b128 v[66:69], v0 offset:64
	v_rcp_f32_e32 v82, v72
	v_rcp_f32_e32 v83, v73
	ds_read_b128 v[72:75], v0 offset:96
	v_rcp_f32_e32 v76, v70
	v_rcp_f32_e32 v77, v71
	s_waitcnt lgkmcnt(0)
	v_rcp_f32_e32 v80, v66
	v_rcp_f32_e32 v81, v67
	v_rcp_f32_e32 v78, v68
	v_rcp_f32_e32 v79, v69
	v_rcp_f32_e32 v72, v72
	v_rcp_f32_e32 v73, v73
	v_rcp_f32_e32 v70, v74
	v_rcp_f32_e32 v71, v75
	v_cndmask_b32_e64 v0, 0, 1, s[2:3]
	v_ashrrev_i32_e32 v89, 31, v88
	v_lshlrev_b64 v[66:67], 8, v[88:89]
	v_lshl_add_u64 v[74:75], s[4:5], 0, v[66:67]
	v_cmp_ne_u32_e64 s[40:41], 1, v0
	s_cbranch_vccz .LBB0_222
	s_andn2_b64 vcc, exec, s[0:1]
	s_cbranch_vccnz .LBB0_186
	s_branch .LBB0_223
